# hyena: per-XCD work queues so every 64-byte output line is written from a single XCD's L2
# speedup vs baseline: 1.0048x; 1.0048x over previous
.LBB0_357:
	s_getreg_b32 s99, hwreg(HW_REG_XCC_ID, 0, 4)
	s_lshl_b32 s100, s99, 5
	s_lshl_b32 s101, s99, 2
	s_mov_b32 s98, 0
	s_cmp_gt_i32 s87, 3
	s_cbranch_scc1 .LBB0_730
	s_load_dword s0, s[92:93], 0x104
	s_waitcnt lgkmcnt(0)
	s_cmp_lt_i32 s0, 4
	s_cbranch_scc1 .LBB0_730
	s_cmp_eq_u32 s87, 3
	s_cbranch_scc0 .LBB0_362
	s_cmpk_lg_i32 s94, 0x100
	s_mov_b64 s[0:1], -1
	s_cbranch_scc1 .LBB0_429

.LBB0_583:
	s_waitcnt vmcnt(0)
	s_barrier
	s_mov_b64 s[0:1], exec
	v_readlane_b32 s2, v232, 4
	v_readlane_b32 s3, v232, 5
	s_and_b64 s[2:3], s[0:1], s[2:3]
	s_mov_b64 exec, s[2:3]
	s_cbranch_execz .LBB0_587
	s_mov_b64 s[4:5], exec
	v_mbcnt_lo_u32_b32 v1, s4, 0
	v_mbcnt_hi_u32_b32 v1, s5, v1
	v_cmp_eq_u32_e32 vcc, 0, v1
	s_and_saveexec_b64 s[2:3], vcc
	s_cbranch_execz .LBB0_586
	s_bcnt1_i32_b64 s4, s[4:5]
	v_mov_b32_e32 v3, s4
	v_readlane_b32 s4, v232, 2
	v_mov_b32_e32 v2, s101
	v_readlane_b32 s5, v232, 3
	s_nop 4
	global_atomic_add v2, v2, v3, s[4:5] sc0
.LBB0_586:
	s_or_b64 exec, exec, s[2:3]
	s_waitcnt vmcnt(0)
	v_readfirstlane_b32 s2, v2
	s_nop 1
	v_add_u32_e32 v1, s2, v1
	s_add_i32 s2, 0, 0x20008
	v_mov_b32_e32 v2, s2
	v_and_b32_e32 v125, 31, v1
	v_bfe_u32 v126, v1, 5, 2
	v_lshl_or_b32 v125, v126, 8, v125
	v_lshrrev_b32_e32 v126, 7, v1
	v_or_b32_e32 v125, s100, v125
	v_lshl_or_b32 v1, v126, 10, v125
	ds_write_b32 v2, v1

.LBB0_607:
	s_lshr_b32 s0, s17, 10
	s_xor_b32 s0, s0, 1
	s_and_b32 s0, s0, 1
	s_and_b32 s16, s17, 0x3ff
	s_cmp_eq_u32 s0, 0
	s_mov_b64 s[0:1], -1
	s_cbranch_scc1 .LBB0_668
	v_mov_b32_e32 v22, v154
	v_mov_b32_e32 v95, 0
	v_cmp_eq_u32_e32 vcc, 0, v22
	s_and_saveexec_b64 s[0:1], vcc
	s_cbranch_execz .LBB0_612
	s_mov_b64 s[4:5], exec
	v_mbcnt_lo_u32_b32 v15, s4, 0
	v_mbcnt_hi_u32_b32 v15, s5, v15
	v_cmp_eq_u32_e32 vcc, 0, v15
	s_and_saveexec_b64 s[2:3], vcc
	s_cbranch_execz .LBB0_611
	s_bcnt1_i32_b64 s4, s[4:5]
	v_mov_b32_e32 v16, s4
	v_readlane_b32 s4, v232, 2
	v_readlane_b32 s5, v232, 3
	s_nop 4
	v_mov_b32_e32 v127, s101
	global_atomic_add v95, v127, v16, s[4:5] sc0

.Lhyf_nowait_607_0:
	v_and_b32_e32 v125, 31, v95
	v_bfe_u32 v126, v95, 5, 2
	v_lshl_or_b32 v125, v126, 8, v125
	v_lshrrev_b32_e32 v126, 7, v95
	v_or_b32_e32 v125, s100, v125
	v_lshl_or_b32 v95, v126, 10, v125
	ds_write_b32 v15, v95

.LBB0_668:
	s_and_b64 vcc, exec, s[0:1]
	s_cbranch_vccz .LBB0_606
	v_mov_b32_e32 v22, v154
	v_mov_b32_e32 v44, 0
	v_cmp_eq_u32_e32 vcc, 0, v22
	s_and_saveexec_b64 s[0:1], vcc
	s_cbranch_execz .LBB0_673
	s_mov_b64 s[4:5], exec
	v_mbcnt_lo_u32_b32 v15, s4, 0
	v_mbcnt_hi_u32_b32 v15, s5, v15
	v_cmp_eq_u32_e32 vcc, 0, v15
	s_and_saveexec_b64 s[2:3], vcc
	s_cbranch_execz .LBB0_672
	s_bcnt1_i32_b64 s4, s[4:5]
	v_mov_b32_e32 v16, s4
	v_readlane_b32 s4, v232, 2
	v_readlane_b32 s5, v232, 3
	s_nop 4
	v_mov_b32_e32 v127, s101
	global_atomic_add v44, v127, v16, s[4:5] sc0

.Lhyf_nowait_607_1:
	v_and_b32_e32 v125, 31, v44
	v_bfe_u32 v126, v44, 5, 2
	v_lshl_or_b32 v125, v126, 8, v125
	v_lshrrev_b32_e32 v126, 7, v44
	v_or_b32_e32 v125, s100, v125
	v_lshl_or_b32 v44, v126, 10, v125
	ds_write_b32 v15, v44

.LBB0_1598:
	s_getreg_b32 s99, hwreg(HW_REG_XCC_ID, 0, 4)
	s_lshl_b32 s100, s99, 5
	s_lshl_b32 s101, s99, 2
	s_mov_b32 s98, 0
	s_cmp_gt_i32 s87, 13
	s_cbranch_scc1 .LBB0_1971
	s_load_dword s0, s[92:93], 0x104
	s_waitcnt lgkmcnt(0)
	s_cmp_lt_i32 s0, 14
	s_cbranch_scc1 .LBB0_1971
	s_cmp_eq_u32 s87, 13
	s_cbranch_scc0 .LBB0_1603
	s_cmpk_lg_i32 s94, 0x100
	s_mov_b64 s[0:1], -1
	s_cbranch_scc1 .LBB0_1670

.LBB0_1824:
	s_add_u32 s10, s90, 0x2c918100
	s_addc_u32 s11, s91, 0
	s_waitcnt vmcnt(0)
	s_barrier
	s_mov_b64 s[0:1], exec
	v_readlane_b32 s2, v232, 4
	v_readlane_b32 s3, v232, 5
	s_and_b64 s[2:3], s[0:1], s[2:3]
	s_mov_b64 exec, s[2:3]
	s_cbranch_execz .LBB0_1828
	s_mov_b64 s[4:5], exec
	v_mbcnt_lo_u32_b32 v1, s4, 0
	v_mbcnt_hi_u32_b32 v1, s5, v1
	v_cmp_eq_u32_e32 vcc, 0, v1
	s_and_saveexec_b64 s[2:3], vcc
	s_cbranch_execz .LBB0_1827
	s_bcnt1_i32_b64 s4, s[4:5]
	v_mov_b32_e32 v2, s101
	v_mov_b32_e32 v3, s4
	global_atomic_add v2, v2, v3, s[10:11] sc0

.LBB0_1848:
	s_lshr_b32 s0, s19, 10
	s_xor_b32 s0, s0, 1
	s_and_b32 s0, s0, 1
	s_and_b32 s18, s19, 0x3ff
	s_cmp_eq_u32 s0, 0
	s_mov_b64 s[0:1], -1
	s_cbranch_scc1 .LBB0_1909
	v_mov_b32_e32 v22, v154
	v_mov_b32_e32 v102, 0
	v_cmp_eq_u32_e32 vcc, 0, v22
	s_and_saveexec_b64 s[0:1], vcc
	s_cbranch_execz .LBB0_1853
	s_mov_b64 s[4:5], exec
	v_mbcnt_lo_u32_b32 v15, s4, 0
	v_mbcnt_hi_u32_b32 v15, s5, v15
	v_cmp_eq_u32_e32 vcc, 0, v15
	s_and_saveexec_b64 s[2:3], vcc
	s_cbranch_execz .LBB0_1852
	s_bcnt1_i32_b64 s4, s[4:5]
	v_mov_b32_e32 v16, s4
	v_mov_b32_e32 v127, s101
	global_atomic_add v102, v127, v16, s[10:11] sc0

.Lhyf_nowait_1848_0:
	v_and_b32_e32 v125, 31, v102
	v_bfe_u32 v126, v102, 5, 2
	v_lshl_or_b32 v125, v126, 8, v125
	v_lshrrev_b32_e32 v126, 7, v102
	v_or_b32_e32 v125, s100, v125
	v_lshl_or_b32 v102, v126, 10, v125
	ds_write_b32 v15, v102

.LBB0_1909:
	s_and_b64 vcc, exec, s[0:1]
	s_cbranch_vccz .LBB0_1847
	v_mov_b32_e32 v22, v154
	v_mov_b32_e32 v44, 0
	v_cmp_eq_u32_e32 vcc, 0, v22
	s_and_saveexec_b64 s[0:1], vcc
	s_cbranch_execz .LBB0_1914
	s_mov_b64 s[4:5], exec
	v_mbcnt_lo_u32_b32 v15, s4, 0
	v_mbcnt_hi_u32_b32 v15, s5, v15
	v_cmp_eq_u32_e32 vcc, 0, v15
	s_and_saveexec_b64 s[2:3], vcc
	s_cbranch_execz .LBB0_1913
	s_bcnt1_i32_b64 s4, s[4:5]
	v_mov_b32_e32 v16, s4
	v_mov_b32_e32 v127, s101
	global_atomic_add v44, v127, v16, s[10:11] sc0
